# grid barrier: non-leader workgroups wait on the top-level generation word directly, per-XCD generation hop removed
# speedup vs baseline: 1.0077x; 1.0077x over previous
; __device__ __forceinline__ unsigned xb_ld(unsigned* p)              { return __hip_atomic_load(p, __ATOMIC_RELAXED, __HIP_MEMORY_SCOPE_AGENT); }
; __device__ __forceinline__ unsigned xb_add(unsigned* p, unsigned v) { return __hip_atomic_fetch_add(p, v, __ATOMIC_RELAXED, __HIP_MEMORY_SCOPE_AGENT); }
; #define XB_SPIN(cond, bar) do { unsigned _sp = 0; while (cond) { __builtin_amdgcn_s_sleep(1); \
;     if ((++_sp & 255u) == 0u) { if (xb_ld(&(bar)[XB_TMO])) break; if (_sp > XB_SPIN_CAP) { atomicAdd(&(bar)[XB_TMO], 1u); break; } } } } while (0)
; __device__ __forceinline__ void xcd_barrier(const XcdBarrier& b) {
;     ...
;         const unsigned old = xb_add(&bar[XB_XSUB(b.x)], 1u);
;         const unsigned gen = old / nloc;
;         if (old + 1u == (gen + 1u) * nloc) {
;             __builtin_amdgcn_fence(__ATOMIC_RELEASE, "agent");
;             asm volatile("s_waitcnt vmcnt(0)" ::: "memory");
;             const unsigned og = xb_add(&bar[XB_TOP], 1u);
;             const unsigned tg = og / nx;
;             if (og + 1u == (tg + 1u) * nx) xb_add(&bar[XB_TOPGEN], 1u);
;             else XB_SPIN(xb_ld(&bar[XB_TOPGEN]) == tg, bar);
;             __builtin_amdgcn_fence(__ATOMIC_ACQUIRE, "agent");
;             xb_add(&bar[XB_XGEN(b.x)], 1u);
;             asm volatile("s_waitcnt vmcnt(0)" ::: "memory");
;         } else {
;             XB_SPIN(xb_ld(&bar[XB_XGEN(b.x)]) == gen, bar);
.LBB0_120:
	s_or_b64 exec, exec, s[12:13]
	v_cvt_f32_u32_e32 v4, v2
	s_waitcnt vmcnt(0)
	v_readfirstlane_b32 s3, v3
	v_sub_u32_e32 v3, 0, v2
	v_rcp_iflag_f32_e32 v4, v4
	v_add_u32_e32 v5, s3, v1
	v_mul_f32_e32 v4, 0x4f7ffffe, v4
	v_cvt_u32_f32_e32 v4, v4
	v_mul_lo_u32 v1, v3, v4
	v_mul_hi_u32 v1, v4, v1
	v_add_u32_e32 v1, v4, v1
	v_mul_hi_u32 v1, v5, v1
	v_mul_lo_u32 v3, v1, v2
	v_sub_u32_e32 v3, v5, v3
	v_add_u32_e32 v4, 1, v1
	v_cmp_ge_u32_e32 vcc, v3, v2
	s_nop 1
	v_cndmask_b32_e32 v1, v1, v4, vcc
	v_sub_u32_e32 v4, v3, v2
	v_cndmask_b32_e32 v3, v3, v4, vcc
	v_add_u32_e32 v4, 1, v1
	v_cmp_ge_u32_e32 vcc, v3, v2
	v_add_u32_e32 v3, 1, v5
	s_nop 0
	v_cndmask_b32_e32 v1, v1, v4, vcc
	v_mul_lo_u32 v4, v2, v1
	v_add_u32_e32 v2, v4, v2
	v_cmp_ne_u32_e32 vcc, v3, v2
	s_and_saveexec_b64 s[10:11], vcc
	s_xor_b64 s[10:11], exec, s[10:11]
	s_cbranch_execz .LBB0_134
	s_waitcnt lgkmcnt(0)
	v_mov_b32_e32 v0, 0
	s_add_u32 s16, s6, 0x2e803500
	s_addc_u32 s17, s7, 0
	global_load_dword v0, v0, s[16:17] sc1
	s_waitcnt vmcnt(0)
	v_cmp_eq_u32_e32 vcc, v0, v1
	s_and_saveexec_b64 s[12:13], vcc
	s_cbranch_execz .LBB0_133
	s_add_u32 s14, s6, 0x2e800200
	s_addc_u32 s15, s7, 0
	s_mov_b32 s3, 1
	s_mov_b64 s[18:19], 0
	v_mov_b32_e32 v0, 0
	s_branch .LBB0_124

; __device__ __forceinline__ unsigned xb_add(unsigned* p, unsigned v) { return __hip_atomic_fetch_add(p, v, __ATOMIC_RELAXED, __HIP_MEMORY_SCOPE_AGENT); }
; __device__ __forceinline__ void xcd_barrier(const XcdBarrier& b) {
;     ...
;             __builtin_amdgcn_fence(__ATOMIC_ACQUIRE, "agent");
;             xb_add(&bar[XB_XGEN(b.x)], 1u);
;             asm volatile("s_waitcnt vmcnt(0)" ::: "memory");
.LBB0_151:
	s_or_b64 exec, exec, s[6:7]
	s_mov_b64 s[6:7], exec
	v_mbcnt_lo_u32_b32 v0, s6, 0
	v_mbcnt_hi_u32_b32 v0, s7, v0
	v_cmp_eq_u32_e32 vcc, 0, v0
	s_waitcnt vmcnt(0)
	buffer_inv sc1
	s_and_saveexec_b64 s[10:11], vcc
	s_cbranch_execz .LBB0_153
	s_bcnt1_i32_b64 s3, s[6:7]
	v_mov_b32_e32 v0, 0x2000
	v_mov_b32_e32 v1, s3
.LBB0_153:
	s_or_b64 exec, exec, s[10:11]
	s_waitcnt vmcnt(0)

; __device__ __forceinline__ unsigned xb_ld(unsigned* p)              { return __hip_atomic_load(p, __ATOMIC_RELAXED, __HIP_MEMORY_SCOPE_AGENT); }
; __device__ __forceinline__ unsigned xb_add(unsigned* p, unsigned v) { return __hip_atomic_fetch_add(p, v, __ATOMIC_RELAXED, __HIP_MEMORY_SCOPE_AGENT); }
; #define XB_SPIN(cond, bar) do { unsigned _sp = 0; while (cond) { __builtin_amdgcn_s_sleep(1); \
;     if ((++_sp & 255u) == 0u) { if (xb_ld(&(bar)[XB_TMO])) break; if (_sp > XB_SPIN_CAP) { atomicAdd(&(bar)[XB_TMO], 1u); break; } } } } while (0)
; __device__ __forceinline__ void xcd_barrier(const XcdBarrier& b) {
;     ...
;         const unsigned old = xb_add(&bar[XB_XSUB(b.x)], 1u);
;         const unsigned gen = old / nloc;
;         if (old + 1u == (gen + 1u) * nloc) {
;             __builtin_amdgcn_fence(__ATOMIC_RELEASE, "agent");
;             asm volatile("s_waitcnt vmcnt(0)" ::: "memory");
;             const unsigned og = xb_add(&bar[XB_TOP], 1u);
;             const unsigned tg = og / nx;
;             if (og + 1u == (tg + 1u) * nx) xb_add(&bar[XB_TOPGEN], 1u);
;             else XB_SPIN(xb_ld(&bar[XB_TOPGEN]) == tg, bar);
;             __builtin_amdgcn_fence(__ATOMIC_ACQUIRE, "agent");
;             xb_add(&bar[XB_XGEN(b.x)], 1u);
;             asm volatile("s_waitcnt vmcnt(0)" ::: "memory");
;         } else {
;             XB_SPIN(xb_ld(&bar[XB_XGEN(b.x)]) == gen, bar);
.LBB0_206:
	s_or_b64 exec, exec, s[12:13]
	v_cvt_f32_u32_e32 v4, v2
	s_waitcnt vmcnt(0)
	v_readfirstlane_b32 s3, v3
	v_sub_u32_e32 v3, 0, v2
	v_rcp_iflag_f32_e32 v4, v4
	v_add_u32_e32 v5, s3, v1
	v_mul_f32_e32 v4, 0x4f7ffffe, v4
	v_cvt_u32_f32_e32 v4, v4
	v_mul_lo_u32 v1, v3, v4
	v_mul_hi_u32 v1, v4, v1
	v_add_u32_e32 v1, v4, v1
	v_mul_hi_u32 v1, v5, v1
	v_mul_lo_u32 v3, v1, v2
	v_sub_u32_e32 v3, v5, v3
	v_add_u32_e32 v4, 1, v1
	v_cmp_ge_u32_e32 vcc, v3, v2
	s_nop 1
	v_cndmask_b32_e32 v1, v1, v4, vcc
	v_sub_u32_e32 v4, v3, v2
	v_cndmask_b32_e32 v3, v3, v4, vcc
	v_add_u32_e32 v4, 1, v1
	v_cmp_ge_u32_e32 vcc, v3, v2
	v_add_u32_e32 v3, 1, v5
	s_nop 0
	v_cndmask_b32_e32 v1, v1, v4, vcc
	v_mul_lo_u32 v4, v2, v1
	v_add_u32_e32 v2, v4, v2
	v_cmp_ne_u32_e32 vcc, v3, v2
	s_and_saveexec_b64 s[10:11], vcc
	s_xor_b64 s[10:11], exec, s[10:11]
	s_cbranch_execz .LBB0_220
	s_waitcnt lgkmcnt(0)
	s_add_u32 s16, s6, 0x2e803500
	s_addc_u32 s17, s7, 0
	global_load_dword v0, v97, s[16:17] sc1
	s_waitcnt vmcnt(0)
	v_cmp_eq_u32_e32 vcc, v0, v1
	s_and_saveexec_b64 s[12:13], vcc
	s_cbranch_execz .LBB0_219
	s_add_u32 s14, s6, 0x2e800200
	s_addc_u32 s15, s7, 0
	s_mov_b32 s3, 1
	s_mov_b64 s[34:35], 0
	s_branch .LBB0_210

; __device__ __forceinline__ unsigned xb_add(unsigned* p, unsigned v) { return __hip_atomic_fetch_add(p, v, __ATOMIC_RELAXED, __HIP_MEMORY_SCOPE_AGENT); }
; __device__ __forceinline__ void xcd_barrier(const XcdBarrier& b) {
;     ...
;             __builtin_amdgcn_fence(__ATOMIC_ACQUIRE, "agent");
;             xb_add(&bar[XB_XGEN(b.x)], 1u);
;             asm volatile("s_waitcnt vmcnt(0)" ::: "memory");
.LBB0_237:
	s_or_b64 exec, exec, s[6:7]
	s_mov_b64 s[6:7], exec
	v_mbcnt_lo_u32_b32 v0, s6, 0
	v_mbcnt_hi_u32_b32 v0, s7, v0
	v_cmp_eq_u32_e32 vcc, 0, v0
	s_waitcnt vmcnt(0)
	buffer_inv sc1
	s_and_saveexec_b64 s[10:11], vcc
	s_cbranch_execz .LBB0_239
	s_bcnt1_i32_b64 s3, s[6:7]
	v_mov_b32_e32 v0, s3
.LBB0_239:
	s_or_b64 exec, exec, s[10:11]
	s_waitcnt vmcnt(0)

; __device__ __forceinline__ unsigned xb_ld(unsigned* p)              { return __hip_atomic_load(p, __ATOMIC_RELAXED, __HIP_MEMORY_SCOPE_AGENT); }
; __device__ __forceinline__ unsigned xb_add(unsigned* p, unsigned v) { return __hip_atomic_fetch_add(p, v, __ATOMIC_RELAXED, __HIP_MEMORY_SCOPE_AGENT); }
; #define XB_SPIN(cond, bar) do { unsigned _sp = 0; while (cond) { __builtin_amdgcn_s_sleep(1); \
;     if ((++_sp & 255u) == 0u) { if (xb_ld(&(bar)[XB_TMO])) break; if (_sp > XB_SPIN_CAP) { atomicAdd(&(bar)[XB_TMO], 1u); break; } } } } while (0)
; __device__ __forceinline__ void xcd_barrier(const XcdBarrier& b) {
;     ...
;         const unsigned old = xb_add(&bar[XB_XSUB(b.x)], 1u);
;         const unsigned gen = old / nloc;
;         if (old + 1u == (gen + 1u) * nloc) {
;             __builtin_amdgcn_fence(__ATOMIC_RELEASE, "agent");
;             asm volatile("s_waitcnt vmcnt(0)" ::: "memory");
;             const unsigned og = xb_add(&bar[XB_TOP], 1u);
;             const unsigned tg = og / nx;
;             if (og + 1u == (tg + 1u) * nx) xb_add(&bar[XB_TOPGEN], 1u);
;             else XB_SPIN(xb_ld(&bar[XB_TOPGEN]) == tg, bar);
;             __builtin_amdgcn_fence(__ATOMIC_ACQUIRE, "agent");
;             xb_add(&bar[XB_XGEN(b.x)], 1u);
;             asm volatile("s_waitcnt vmcnt(0)" ::: "memory");
;         } else {
;             XB_SPIN(xb_ld(&bar[XB_XGEN(b.x)]) == gen, bar);
.LBB0_306:
	s_or_b64 exec, exec, s[12:13]
	v_cvt_f32_u32_e32 v4, v2
	s_waitcnt vmcnt(0)
	v_readfirstlane_b32 s2, v3
	v_sub_u32_e32 v3, 0, v2
	v_rcp_iflag_f32_e32 v4, v4
	v_add_u32_e32 v5, s2, v1
	v_mul_f32_e32 v4, 0x4f7ffffe, v4
	v_cvt_u32_f32_e32 v4, v4
	v_mul_lo_u32 v1, v3, v4
	v_mul_hi_u32 v1, v4, v1
	v_add_u32_e32 v1, v4, v1
	v_mul_hi_u32 v1, v5, v1
	v_mul_lo_u32 v3, v1, v2
	v_sub_u32_e32 v3, v5, v3
	v_add_u32_e32 v4, 1, v1
	v_cmp_ge_u32_e32 vcc, v3, v2
	s_nop 1
	v_cndmask_b32_e32 v1, v1, v4, vcc
	v_sub_u32_e32 v4, v3, v2
	v_cndmask_b32_e32 v3, v3, v4, vcc
	v_add_u32_e32 v4, 1, v1
	v_cmp_ge_u32_e32 vcc, v3, v2
	v_add_u32_e32 v3, 1, v5
	s_nop 0
	v_cndmask_b32_e32 v1, v1, v4, vcc
	v_mul_lo_u32 v4, v2, v1
	v_add_u32_e32 v2, v4, v2
	v_cmp_ne_u32_e32 vcc, v3, v2
	s_and_saveexec_b64 s[2:3], vcc
	s_xor_b64 s[10:11], exec, s[2:3]
	s_cbranch_execz .LBB0_320
	s_waitcnt lgkmcnt(0)
	s_add_u32 s16, s6, 0x2e803500
	s_addc_u32 s17, s7, 0
	global_load_dword v0, v97, s[16:17] sc1
	s_waitcnt vmcnt(0)
	v_cmp_eq_u32_e32 vcc, v0, v1
	s_and_saveexec_b64 s[12:13], vcc
	s_cbranch_execz .LBB0_319
	s_add_u32 s14, s6, 0x2e800200
	s_addc_u32 s15, s7, 0
	s_mov_b32 s2, 1
	s_mov_b64 s[34:35], 0
	s_branch .LBB0_310

; __device__ __forceinline__ unsigned xb_add(unsigned* p, unsigned v) { return __hip_atomic_fetch_add(p, v, __ATOMIC_RELAXED, __HIP_MEMORY_SCOPE_AGENT); }
; __device__ __forceinline__ void xcd_barrier(const XcdBarrier& b) {
;     ...
;             __builtin_amdgcn_fence(__ATOMIC_ACQUIRE, "agent");
;             xb_add(&bar[XB_XGEN(b.x)], 1u);
;             asm volatile("s_waitcnt vmcnt(0)" ::: "memory");
.LBB0_337:
	s_or_b64 exec, exec, s[6:7]
	s_mov_b64 s[6:7], exec
	v_mbcnt_lo_u32_b32 v0, s6, 0
	v_mbcnt_hi_u32_b32 v0, s7, v0
	v_cmp_eq_u32_e32 vcc, 0, v0
	s_waitcnt vmcnt(0)
	buffer_inv sc1
	s_and_saveexec_b64 s[10:11], vcc
	s_cbranch_execz .LBB0_339
	s_bcnt1_i32_b64 s2, s[6:7]
	v_mov_b32_e32 v0, s2
.LBB0_339:
	s_or_b64 exec, exec, s[10:11]
	s_waitcnt vmcnt(0)

; __device__ __forceinline__ unsigned xb_add(unsigned* p, unsigned v) { return __hip_atomic_fetch_add(p, v, __ATOMIC_RELAXED, __HIP_MEMORY_SCOPE_AGENT); }
; __device__ __forceinline__ void xcd_barrier(const XcdBarrier& b) {
;     ...
;             __builtin_amdgcn_fence(__ATOMIC_ACQUIRE, "agent");
;             xb_add(&bar[XB_XGEN(b.x)], 1u);
;             asm volatile("s_waitcnt vmcnt(0)" ::: "memory");
.LBB0_453:
	s_or_b64 exec, exec, s[6:7]
	s_mov_b64 s[6:7], exec
	v_mbcnt_lo_u32_b32 v0, s6, 0
	v_mbcnt_hi_u32_b32 v0, s7, v0
	v_cmp_eq_u32_e32 vcc, 0, v0
	s_waitcnt vmcnt(0)
	buffer_inv sc1
	s_and_saveexec_b64 s[10:11], vcc
	s_cbranch_execz .LBB0_455
	s_bcnt1_i32_b64 s3, s[6:7]
	v_mov_b32_e32 v0, s3
.LBB0_455:
	s_or_b64 exec, exec, s[10:11]
	s_waitcnt vmcnt(0)

; __device__ __forceinline__ unsigned xb_add(unsigned* p, unsigned v) { return __hip_atomic_fetch_add(p, v, __ATOMIC_RELAXED, __HIP_MEMORY_SCOPE_AGENT); }
; __device__ __forceinline__ void xcd_barrier(const XcdBarrier& b) {
;     ...
;             __builtin_amdgcn_fence(__ATOMIC_ACQUIRE, "agent");
;             xb_add(&bar[XB_XGEN(b.x)], 1u);
;             asm volatile("s_waitcnt vmcnt(0)" ::: "memory");
.LBB0_540:
	s_or_b64 exec, exec, s[6:7]
	s_mov_b64 s[6:7], exec
	v_mbcnt_lo_u32_b32 v0, s6, 0
	v_mbcnt_hi_u32_b32 v0, s7, v0
	v_cmp_eq_u32_e32 vcc, 0, v0
	s_waitcnt vmcnt(0)
	buffer_inv sc1
	s_and_saveexec_b64 s[10:11], vcc
	s_cbranch_execz .LBB0_542
	s_bcnt1_i32_b64 s3, s[6:7]
	v_mov_b32_e32 v0, s3
.LBB0_542:
	s_or_b64 exec, exec, s[10:11]
	s_waitcnt vmcnt(0)

; __device__ __forceinline__ unsigned xb_ld(unsigned* p)              { return __hip_atomic_load(p, __ATOMIC_RELAXED, __HIP_MEMORY_SCOPE_AGENT); }
; __device__ __forceinline__ unsigned xb_add(unsigned* p, unsigned v) { return __hip_atomic_fetch_add(p, v, __ATOMIC_RELAXED, __HIP_MEMORY_SCOPE_AGENT); }
; #define XB_SPIN(cond, bar) do { unsigned _sp = 0; while (cond) { __builtin_amdgcn_s_sleep(1); \
;     if ((++_sp & 255u) == 0u) { if (xb_ld(&(bar)[XB_TMO])) break; if (_sp > XB_SPIN_CAP) { atomicAdd(&(bar)[XB_TMO], 1u); break; } } } } while (0)
; __device__ __forceinline__ void xcd_barrier(const XcdBarrier& b) {
;     ...
;         const unsigned old = xb_add(&bar[XB_XSUB(b.x)], 1u);
;         const unsigned gen = old / nloc;
;         if (old + 1u == (gen + 1u) * nloc) {
;             __builtin_amdgcn_fence(__ATOMIC_RELEASE, "agent");
;             asm volatile("s_waitcnt vmcnt(0)" ::: "memory");
;             const unsigned og = xb_add(&bar[XB_TOP], 1u);
;             const unsigned tg = og / nx;
;             if (og + 1u == (tg + 1u) * nx) xb_add(&bar[XB_TOPGEN], 1u);
;             else XB_SPIN(xb_ld(&bar[XB_TOPGEN]) == tg, bar);
;             __builtin_amdgcn_fence(__ATOMIC_ACQUIRE, "agent");
;             xb_add(&bar[XB_XGEN(b.x)], 1u);
;             asm volatile("s_waitcnt vmcnt(0)" ::: "memory");
;         } else {
;             XB_SPIN(xb_ld(&bar[XB_XGEN(b.x)]) == gen, bar);
.LBB0_672:
	s_or_b64 exec, exec, s[14:15]
	v_cvt_f32_u32_e32 v4, v2
	s_waitcnt vmcnt(0)
	v_readfirstlane_b32 s3, v3
	v_sub_u32_e32 v3, 0, v2
	v_rcp_iflag_f32_e32 v4, v4
	v_add_u32_e32 v5, s3, v1
	v_mul_f32_e32 v4, 0x4f7ffffe, v4
	v_cvt_u32_f32_e32 v4, v4
	v_mul_lo_u32 v1, v3, v4
	v_mul_hi_u32 v1, v4, v1
	v_add_u32_e32 v1, v4, v1
	v_mul_hi_u32 v1, v5, v1
	v_mul_lo_u32 v3, v1, v2
	v_sub_u32_e32 v3, v5, v3
	v_add_u32_e32 v4, 1, v1
	v_cmp_ge_u32_e32 vcc, v3, v2
	s_nop 1
	v_cndmask_b32_e32 v1, v1, v4, vcc
	v_sub_u32_e32 v4, v3, v2
	v_cndmask_b32_e32 v3, v3, v4, vcc
	v_add_u32_e32 v4, 1, v1
	v_cmp_ge_u32_e32 vcc, v3, v2
	v_add_u32_e32 v3, 1, v5
	s_nop 0
	v_cndmask_b32_e32 v1, v1, v4, vcc
	v_mul_lo_u32 v4, v2, v1
	v_add_u32_e32 v2, v4, v2
	v_cmp_ne_u32_e32 vcc, v3, v2
	s_and_saveexec_b64 s[10:11], vcc
	s_xor_b64 s[10:11], exec, s[10:11]
	s_cbranch_execz .LBB0_703
	s_waitcnt lgkmcnt(0)
	s_add_u32 s34, s6, 0x2e803500
	s_addc_u32 s35, s7, 0
	global_load_dword v0, v97, s[34:35] sc1
	s_waitcnt vmcnt(0)
	v_cmp_eq_u32_e32 vcc, v0, v1
	s_and_saveexec_b64 s[14:15], vcc
	s_cbranch_execz .LBB0_702
	s_add_u32 s16, s6, 0x2e800200
	s_addc_u32 s17, s7, 0
	s_mov_b32 s3, 1
	s_mov_b64 s[52:53], 0
	s_branch .LBB0_676

; __device__ __forceinline__ unsigned xb_add(unsigned* p, unsigned v) { return __hip_atomic_fetch_add(p, v, __ATOMIC_RELAXED, __HIP_MEMORY_SCOPE_AGENT); }
; __device__ __forceinline__ void xcd_barrier(const XcdBarrier& b) {
;     ...
;             __builtin_amdgcn_fence(__ATOMIC_ACQUIRE, "agent");
;             xb_add(&bar[XB_XGEN(b.x)], 1u);
;             asm volatile("s_waitcnt vmcnt(0)" ::: "memory");
.LBB0_737:
	s_or_b64 exec, exec, s[6:7]
	s_mov_b64 s[6:7], exec
	v_mbcnt_lo_u32_b32 v0, s6, 0
	v_mbcnt_hi_u32_b32 v0, s7, v0
	v_cmp_eq_u32_e32 vcc, 0, v0
	s_waitcnt vmcnt(0)
	buffer_inv sc1
	s_and_saveexec_b64 s[10:11], vcc
	s_cbranch_execz .LBB0_739
	s_bcnt1_i32_b64 s3, s[6:7]
	v_mov_b32_e32 v0, s3
.LBB0_739:
	s_or_b64 exec, exec, s[10:11]
	s_waitcnt vmcnt(0)

; __device__ __forceinline__ unsigned xb_add(unsigned* p, unsigned v) { return __hip_atomic_fetch_add(p, v, __ATOMIC_RELAXED, __HIP_MEMORY_SCOPE_AGENT); }
; __device__ __forceinline__ void xcd_barrier(const XcdBarrier& b) {
;     ...
;             __builtin_amdgcn_fence(__ATOMIC_ACQUIRE, "agent");
;             xb_add(&bar[XB_XGEN(b.x)], 1u);
;             asm volatile("s_waitcnt vmcnt(0)" ::: "memory");
.LBB0_1048:
	s_or_b64 exec, exec, s[6:7]
	s_mov_b64 s[6:7], exec
	v_mbcnt_lo_u32_b32 v0, s6, 0
	v_mbcnt_hi_u32_b32 v0, s7, v0
	v_cmp_eq_u32_e32 vcc, 0, v0
	s_waitcnt vmcnt(0)
	buffer_inv sc1
	s_and_saveexec_b64 s[10:11], vcc
	s_cbranch_execz .LBB0_1050
	s_bcnt1_i32_b64 s2, s[6:7]
	v_mov_b32_e32 v0, s2
.LBB0_1050:
	s_or_b64 exec, exec, s[10:11]
	s_waitcnt vmcnt(0)

; __device__ __forceinline__ unsigned xb_add(unsigned* p, unsigned v) { return __hip_atomic_fetch_add(p, v, __ATOMIC_RELAXED, __HIP_MEMORY_SCOPE_AGENT); }
; __device__ __forceinline__ void xcd_barrier(const XcdBarrier& b) {
;     ...
;             __builtin_amdgcn_fence(__ATOMIC_ACQUIRE, "agent");
;             xb_add(&bar[XB_XGEN(b.x)], 1u);
;             asm volatile("s_waitcnt vmcnt(0)" ::: "memory");
.LBB0_1271:
	s_or_b64 exec, exec, s[6:7]
	s_mov_b64 s[6:7], exec
	v_mbcnt_lo_u32_b32 v0, s6, 0
	v_mbcnt_hi_u32_b32 v0, s7, v0
	v_cmp_eq_u32_e32 vcc, 0, v0
	s_waitcnt vmcnt(0)
	buffer_inv sc1
	s_and_saveexec_b64 s[10:11], vcc
	s_cbranch_execz .LBB0_1273
	s_bcnt1_i32_b64 s3, s[6:7]
	v_mov_b32_e32 v0, s3
.LBB0_1273:
	s_or_b64 exec, exec, s[10:11]
	s_waitcnt vmcnt(0)

; __device__ __forceinline__ unsigned xb_add(unsigned* p, unsigned v) { return __hip_atomic_fetch_add(p, v, __ATOMIC_RELAXED, __HIP_MEMORY_SCOPE_AGENT); }
; __device__ __forceinline__ void xcd_barrier(const XcdBarrier& b) {
;     ...
;             __builtin_amdgcn_fence(__ATOMIC_ACQUIRE, "agent");
;             xb_add(&bar[XB_XGEN(b.x)], 1u);
;             asm volatile("s_waitcnt vmcnt(0)" ::: "memory");
.LBB0_1339:
	s_or_b64 exec, exec, s[6:7]
	s_mov_b64 s[6:7], exec
	v_mbcnt_lo_u32_b32 v0, s6, 0
	v_mbcnt_hi_u32_b32 v0, s7, v0
	v_cmp_eq_u32_e32 vcc, 0, v0
	s_waitcnt vmcnt(0)
	buffer_inv sc1
	s_and_saveexec_b64 s[10:11], vcc
	s_cbranch_execz .LBB0_1341
	s_bcnt1_i32_b64 s3, s[6:7]
	v_mov_b32_e32 v0, s3
.LBB0_1341:
	s_or_b64 exec, exec, s[10:11]
	s_waitcnt vmcnt(0)

; __device__ __forceinline__ unsigned xb_add(unsigned* p, unsigned v) { return __hip_atomic_fetch_add(p, v, __ATOMIC_RELAXED, __HIP_MEMORY_SCOPE_AGENT); }
; __device__ __forceinline__ void xcd_barrier(const XcdBarrier& b) {
;     ...
;             __builtin_amdgcn_fence(__ATOMIC_ACQUIRE, "agent");
;             xb_add(&bar[XB_XGEN(b.x)], 1u);
;             asm volatile("s_waitcnt vmcnt(0)" ::: "memory");
.LBB0_1490:
	s_bcnt1_i32_b64 s2, s[6:7]
	v_mov_b32_e32 v0, s2
	s_getpc_b64 s[98:99]

; __device__ __forceinline__ unsigned xb_add(unsigned* p, unsigned v) { return __hip_atomic_fetch_add(p, v, __ATOMIC_RELAXED, __HIP_MEMORY_SCOPE_AGENT); }
; __device__ __forceinline__ void xcd_barrier(const XcdBarrier& b) {
;     ...
;             __builtin_amdgcn_fence(__ATOMIC_ACQUIRE, "agent");
;             xb_add(&bar[XB_XGEN(b.x)], 1u);
;             asm volatile("s_waitcnt vmcnt(0)" ::: "memory");
.LBB0_1495:
	s_or_b64 exec, exec, s[6:7]
	s_mov_b64 s[6:7], exec
	v_mbcnt_lo_u32_b32 v0, s6, 0
	v_mbcnt_hi_u32_b32 v0, s7, v0
	v_cmp_eq_u32_e32 vcc, 0, v0
	s_waitcnt vmcnt(0)
	buffer_inv sc1
	s_and_saveexec_b64 s[10:11], vcc
	s_cbranch_execz .LBB0_1497
	s_bcnt1_i32_b64 s2, s[6:7]
	v_mov_b32_e32 v0, s2
.LBB0_1497:
	s_or_b64 exec, exec, s[10:11]
	s_waitcnt vmcnt(0)
